# combination + XCD leader invalidates right after its write-back (no trailing waits)
# speedup vs baseline: 1.0030x; 1.0030x over previous
; __device__ __forceinline__ unsigned xb_add(unsigned* p, unsigned v) { return __hip_atomic_fetch_add(p, v, __ATOMIC_RELAXED, __HIP_MEMORY_SCOPE_AGENT); }
; __device__ __forceinline__ void xcd_barrier(const XcdBarrier& b) {
;     ...
;         if (old + 1u == (gen + 1u) * nloc) {
;             __builtin_amdgcn_fence(__ATOMIC_RELEASE, "agent");
;             asm volatile("s_waitcnt vmcnt(0)" ::: "memory");
;             const unsigned og = xb_add(&bar[XB_TOP], 1u);
.LBB0_107:
	s_andn2_saveexec_b64 s[8:9], s[8:9]
	s_cbranch_execz .LBB0_127
	s_mov_b64 s[8:9], exec
	buffer_wbl2 sc1
	s_waitcnt lgkmcnt(0)
	s_waitcnt vmcnt(0)
	buffer_inv sc1
	v_mbcnt_lo_u32_b32 v2, s8, 0
	v_mbcnt_hi_u32_b32 v2, s9, v2
	v_cmp_eq_u32_e32 vcc, 0, v2
	s_and_saveexec_b64 s[14:15], vcc
	s_cbranch_execz .LBB0_110
	s_bcnt1_i32_b64 s3, s[8:9]
	v_mov_b32_e32 v3, 0x4000
	v_mov_b32_e32 v4, s3
	global_atomic_add v3, v3, v4, s[30:31] offset:1024 sc0

; __device__ __forceinline__ unsigned xb_ld(unsigned* p)              { return __hip_atomic_load(p, __ATOMIC_RELAXED, __HIP_MEMORY_SCOPE_AGENT); }
; __device__ __forceinline__ unsigned xb_add(unsigned* p, unsigned v) { return __hip_atomic_fetch_add(p, v, __ATOMIC_RELAXED, __HIP_MEMORY_SCOPE_AGENT); }
; #define XB_SPIN(cond, bar) do { unsigned _sp = 0; while (cond) { __builtin_amdgcn_s_sleep(1); \
;     if ((++_sp & 255u) == 0u) { if (xb_ld(&(bar)[XB_TMO])) break; if (_sp > XB_SPIN_CAP) { atomicAdd(&(bar)[XB_TMO], 1u); break; } } } } while (0)
; __device__ __forceinline__ void xcd_barrier(const XcdBarrier& b) {
;     ...
;             const unsigned tg = og / nx;
;             if (og + 1u == (tg + 1u) * nx) xb_add(&bar[XB_TOPGEN], 1u);
;             else XB_SPIN(xb_ld(&bar[XB_TOPGEN]) == tg, bar);
;             __builtin_amdgcn_fence(__ATOMIC_ACQUIRE, "agent");
;             xb_add(&bar[XB_XGEN(b.x)], 1u);
;             asm volatile("s_waitcnt vmcnt(0)" ::: "memory");
.LBB0_124:
	s_or_b64 exec, exec, s[8:9]
	s_mov_b64 s[8:9], exec
	v_mbcnt_lo_u32_b32 v1, s8, 0
	v_mbcnt_hi_u32_b32 v1, s9, v1
	v_cmp_eq_u32_e32 vcc, 0, v1
	s_and_saveexec_b64 s[14:15], vcc
	s_cbranch_execz .LBB0_126
	s_bcnt1_i32_b64 s3, s[8:9]
	v_mov_b32_e32 v1, 0x2000
	v_mov_b32_e32 v2, s3
.LBB0_126:
	s_or_b64 exec, exec, s[14:15]
.LBB0_127:
	s_or_b64 exec, exec, s[4:5]
	s_waitcnt lgkmcnt(0)
	s_barrier

; __device__ __forceinline__ unsigned xb_ld(unsigned* p)              { return __hip_atomic_load(p, __ATOMIC_RELAXED, __HIP_MEMORY_SCOPE_AGENT); }
; __device__ __forceinline__ unsigned xb_add(unsigned* p, unsigned v) { return __hip_atomic_fetch_add(p, v, __ATOMIC_RELAXED, __HIP_MEMORY_SCOPE_AGENT); }
; #define XB_SPIN(cond, bar) do { unsigned _sp = 0; while (cond) { __builtin_amdgcn_s_sleep(1); \
;     if ((++_sp & 255u) == 0u) { if (xb_ld(&(bar)[XB_TMO])) break; if (_sp > XB_SPIN_CAP) { atomicAdd(&(bar)[XB_TMO], 1u); break; } } } } while (0)
; __device__ __forceinline__ void xcd_barrier(const XcdBarrier& b) {
;     ...
;             xb_add(&bar[XB_XGEN(b.x)], 1u);
;             asm volatile("s_waitcnt vmcnt(0)" ::: "memory");
;         } else {
;             XB_SPIN(xb_ld(&bar[XB_XGEN(b.x)]) == gen, bar);
;             __builtin_amdgcn_fence(__ATOMIC_ACQUIRE, "agent");
;             asm volatile("s_waitcnt vmcnt(0)" ::: "memory");
;         }
;     }
;     __syncthreads();
.LBB0_219:
	s_or_b64 exec, exec, s[14:15]
.LBB0_220:
	s_or_b64 exec, exec, s[0:1]
	s_waitcnt lgkmcnt(0)
	s_barrier

; __device__ __forceinline__ unsigned xb_add(unsigned* p, unsigned v) { return __hip_atomic_fetch_add(p, v, __ATOMIC_RELAXED, __HIP_MEMORY_SCOPE_AGENT); }
; __device__ __forceinline__ void xcd_barrier(const XcdBarrier& b) {
;     ...
;         if (old + 1u == (gen + 1u) * nloc) {
;             __builtin_amdgcn_fence(__ATOMIC_RELEASE, "agent");
;             asm volatile("s_waitcnt vmcnt(0)" ::: "memory");
;             const unsigned og = xb_add(&bar[XB_TOP], 1u);
.LBB0_505:
	s_andn2_saveexec_b64 s[8:9], s[8:9]
	s_cbranch_execz .LBB0_525
	s_mov_b64 s[8:9], exec
	buffer_wbl2 sc1
	s_waitcnt lgkmcnt(0)
	s_waitcnt vmcnt(0)
	buffer_inv sc1
	v_mbcnt_lo_u32_b32 v2, s8, 0
	v_mbcnt_hi_u32_b32 v2, s9, v2
	v_cmp_eq_u32_e32 vcc, 0, v2
	s_and_saveexec_b64 s[10:11], vcc
	s_cbranch_execz .LBB0_508
	s_bcnt1_i32_b64 s3, s[8:9]
	v_mov_b32_e32 v3, 0x4000
	v_mov_b32_e32 v4, s3
	global_atomic_add v3, v3, v4, s[30:31] offset:1024 sc0

; __device__ __forceinline__ unsigned xb_ld(unsigned* p)              { return __hip_atomic_load(p, __ATOMIC_RELAXED, __HIP_MEMORY_SCOPE_AGENT); }
; __device__ __forceinline__ unsigned xb_add(unsigned* p, unsigned v) { return __hip_atomic_fetch_add(p, v, __ATOMIC_RELAXED, __HIP_MEMORY_SCOPE_AGENT); }
; #define XB_SPIN(cond, bar) do { unsigned _sp = 0; while (cond) { __builtin_amdgcn_s_sleep(1); \
;     if ((++_sp & 255u) == 0u) { if (xb_ld(&(bar)[XB_TMO])) break; if (_sp > XB_SPIN_CAP) { atomicAdd(&(bar)[XB_TMO], 1u); break; } } } } while (0)
; __device__ __forceinline__ void xcd_barrier(const XcdBarrier& b) {
;     ...
;             const unsigned tg = og / nx;
;             if (og + 1u == (tg + 1u) * nx) xb_add(&bar[XB_TOPGEN], 1u);
;             else XB_SPIN(xb_ld(&bar[XB_TOPGEN]) == tg, bar);
;             __builtin_amdgcn_fence(__ATOMIC_ACQUIRE, "agent");
;             xb_add(&bar[XB_XGEN(b.x)], 1u);
;             asm volatile("s_waitcnt vmcnt(0)" ::: "memory");
.LBB0_522:
	s_or_b64 exec, exec, s[8:9]
	s_mov_b64 s[8:9], exec
	v_mbcnt_lo_u32_b32 v1, s8, 0
	v_mbcnt_hi_u32_b32 v1, s9, v1
	v_cmp_eq_u32_e32 vcc, 0, v1
	s_and_saveexec_b64 s[10:11], vcc
	s_cbranch_execz .LBB0_524
	s_bcnt1_i32_b64 s3, s[8:9]
	v_mov_b32_e32 v1, 0x2000
	v_mov_b32_e32 v2, s3
.LBB0_524:
	s_or_b64 exec, exec, s[10:11]
.LBB0_525:
	s_or_b64 exec, exec, s[0:1]
	s_waitcnt lgkmcnt(0)
	s_barrier

; __device__ __forceinline__ unsigned xb_ld(unsigned* p)              { return __hip_atomic_load(p, __ATOMIC_RELAXED, __HIP_MEMORY_SCOPE_AGENT); }
; __device__ __forceinline__ unsigned xb_add(unsigned* p, unsigned v) { return __hip_atomic_fetch_add(p, v, __ATOMIC_RELAXED, __HIP_MEMORY_SCOPE_AGENT); }
; #define XB_SPIN(cond, bar) do { unsigned _sp = 0; while (cond) { __builtin_amdgcn_s_sleep(1); \
;     if ((++_sp & 255u) == 0u) { if (xb_ld(&(bar)[XB_TMO])) break; if (_sp > XB_SPIN_CAP) { atomicAdd(&(bar)[XB_TMO], 1u); break; } } } } while (0)
; __device__ __forceinline__ void xcd_barrier(const XcdBarrier& b) {
;     ...
;             xb_add(&bar[XB_XGEN(b.x)], 1u);
;             asm volatile("s_waitcnt vmcnt(0)" ::: "memory");
;         } else {
;             XB_SPIN(xb_ld(&bar[XB_XGEN(b.x)]) == gen, bar);
;             __builtin_amdgcn_fence(__ATOMIC_ACQUIRE, "agent");
;             asm volatile("s_waitcnt vmcnt(0)" ::: "memory");
;         }
;     }
;     __syncthreads();
.LBB0_596:
	s_or_b64 exec, exec, s[10:11]
.LBB0_597:
	s_or_b64 exec, exec, s[4:5]
	s_waitcnt lgkmcnt(0)
	s_barrier

; __device__ __forceinline__ unsigned xb_ld(unsigned* p)              { return __hip_atomic_load(p, __ATOMIC_RELAXED, __HIP_MEMORY_SCOPE_AGENT); }
; __device__ __forceinline__ unsigned xb_add(unsigned* p, unsigned v) { return __hip_atomic_fetch_add(p, v, __ATOMIC_RELAXED, __HIP_MEMORY_SCOPE_AGENT); }
; #define XB_SPIN(cond, bar) do { unsigned _sp = 0; while (cond) { __builtin_amdgcn_s_sleep(1); \
;     if ((++_sp & 255u) == 0u) { if (xb_ld(&(bar)[XB_TMO])) break; if (_sp > XB_SPIN_CAP) { atomicAdd(&(bar)[XB_TMO], 1u); break; } } } } while (0)
; __device__ __forceinline__ void xcd_barrier(const XcdBarrier& b) {
;     ...
;             xb_add(&bar[XB_XGEN(b.x)], 1u);
;             asm volatile("s_waitcnt vmcnt(0)" ::: "memory");
;         } else {
;             XB_SPIN(xb_ld(&bar[XB_XGEN(b.x)]) == gen, bar);
;             __builtin_amdgcn_fence(__ATOMIC_ACQUIRE, "agent");
;             asm volatile("s_waitcnt vmcnt(0)" ::: "memory");
;         }
;     }
;     __syncthreads();
.LBB0_695:
	s_or_b64 exec, exec, s[10:11]
.LBB0_696:
	s_or_b64 exec, exec, s[0:1]
	s_waitcnt lgkmcnt(0)
	s_barrier

; __device__ __forceinline__ unsigned xb_ld(unsigned* p)              { return __hip_atomic_load(p, __ATOMIC_RELAXED, __HIP_MEMORY_SCOPE_AGENT); }
; __device__ __forceinline__ unsigned xb_add(unsigned* p, unsigned v) { return __hip_atomic_fetch_add(p, v, __ATOMIC_RELAXED, __HIP_MEMORY_SCOPE_AGENT); }
; #define XB_SPIN(cond, bar) do { unsigned _sp = 0; while (cond) { __builtin_amdgcn_s_sleep(1); \
;     if ((++_sp & 255u) == 0u) { if (xb_ld(&(bar)[XB_TMO])) break; if (_sp > XB_SPIN_CAP) { atomicAdd(&(bar)[XB_TMO], 1u); break; } } } } while (0)
; __device__ __forceinline__ void xcd_barrier(const XcdBarrier& b) {
;     ...
;             xb_add(&bar[XB_XGEN(b.x)], 1u);
;             asm volatile("s_waitcnt vmcnt(0)" ::: "memory");
;         } else {
;             XB_SPIN(xb_ld(&bar[XB_XGEN(b.x)]) == gen, bar);
;             __builtin_amdgcn_fence(__ATOMIC_ACQUIRE, "agent");
;             asm volatile("s_waitcnt vmcnt(0)" ::: "memory");
;         }
;     }
;     __syncthreads();
.LBB0_788:
	s_or_b64 exec, exec, s[10:11]
.LBB0_789:
	s_or_b64 exec, exec, s[0:1]
	s_waitcnt lgkmcnt(0)
	s_barrier

; __device__ __forceinline__ unsigned xb_add(unsigned* p, unsigned v) { return __hip_atomic_fetch_add(p, v, __ATOMIC_RELAXED, __HIP_MEMORY_SCOPE_AGENT); }
; __device__ __forceinline__ void xcd_barrier(const XcdBarrier& b) {
;     ...
;         if (old + 1u == (gen + 1u) * nloc) {
;             __builtin_amdgcn_fence(__ATOMIC_RELEASE, "agent");
;             asm volatile("s_waitcnt vmcnt(0)" ::: "memory");
;             const unsigned og = xb_add(&bar[XB_TOP], 1u);
.LBB0_847:
	s_andn2_saveexec_b64 s[6:7], s[6:7]
	s_cbranch_execz .LBB0_867
	s_mov_b64 s[6:7], exec
	buffer_wbl2 sc1
	s_waitcnt lgkmcnt(0)
	s_waitcnt vmcnt(0)
	buffer_inv sc1
	v_mbcnt_lo_u32_b32 v2, s6, 0
	v_mbcnt_hi_u32_b32 v2, s7, v2
	v_cmp_eq_u32_e32 vcc, 0, v2
	s_and_saveexec_b64 s[8:9], vcc
	s_cbranch_execz .LBB0_850
	s_bcnt1_i32_b64 s3, s[6:7]
	v_mov_b32_e32 v3, 0x4000
	v_mov_b32_e32 v4, s3
	global_atomic_add v3, v3, v4, s[30:31] offset:1024 sc0

; __device__ __forceinline__ unsigned xb_ld(unsigned* p)              { return __hip_atomic_load(p, __ATOMIC_RELAXED, __HIP_MEMORY_SCOPE_AGENT); }
; __device__ __forceinline__ unsigned xb_add(unsigned* p, unsigned v) { return __hip_atomic_fetch_add(p, v, __ATOMIC_RELAXED, __HIP_MEMORY_SCOPE_AGENT); }
; #define XB_SPIN(cond, bar) do { unsigned _sp = 0; while (cond) { __builtin_amdgcn_s_sleep(1); \
;     if ((++_sp & 255u) == 0u) { if (xb_ld(&(bar)[XB_TMO])) break; if (_sp > XB_SPIN_CAP) { atomicAdd(&(bar)[XB_TMO], 1u); break; } } } } while (0)
; __device__ __forceinline__ void xcd_barrier(const XcdBarrier& b) {
;     ...
;             const unsigned tg = og / nx;
;             if (og + 1u == (tg + 1u) * nx) xb_add(&bar[XB_TOPGEN], 1u);
;             else XB_SPIN(xb_ld(&bar[XB_TOPGEN]) == tg, bar);
;             __builtin_amdgcn_fence(__ATOMIC_ACQUIRE, "agent");
;             xb_add(&bar[XB_XGEN(b.x)], 1u);
;             asm volatile("s_waitcnt vmcnt(0)" ::: "memory");
.LBB0_864:
	s_or_b64 exec, exec, s[6:7]
	s_mov_b64 s[6:7], exec
	v_mbcnt_lo_u32_b32 v1, s6, 0
	v_mbcnt_hi_u32_b32 v1, s7, v1
	v_cmp_eq_u32_e32 vcc, 0, v1
	s_and_saveexec_b64 s[8:9], vcc
	s_cbranch_execz .LBB0_866
	s_bcnt1_i32_b64 s3, s[6:7]
	v_mov_b32_e32 v1, 0x2000
	v_mov_b32_e32 v2, s3
.LBB0_866:
	s_or_b64 exec, exec, s[8:9]
.LBB0_867:
	s_or_b64 exec, exec, s[0:1]
	s_waitcnt lgkmcnt(0)
	s_barrier
